# weight-set-1 transposes: the down-projection items move to the workgroups idle in layer 0's third attention round (w_in layer-0 tail no longer critical); hand-scheduled w_in epilogues both layers
# baseline (speedup 1.0000x reference)
.LBB0_300:
	s_abs_i32 s36, s94
	v_cvt_f32_u32_e32 v1, s36
	s_sub_i32 s3, 0, s36
	s_add_i32 s0, s94, 0x1af
	s_ashr_i32 s1, s0, 31
	v_rcp_iflag_f32_e32 v1, v1
	s_abs_i32 s0, s0
	s_ashr_i32 s95, s94, 31
	s_xor_b32 s1, s1, s95
	v_mul_f32_e32 v1, 0x4f7ffffe, v1
	v_cvt_u32_f32_e32 v1, v1
	v_mov_b32_e32 v2, v0
	v_readfirstlane_b32 s4, v1
	s_mul_i32 s3, s3, s4
	s_mul_hi_u32 s3, s4, s3
	s_add_i32 s3, s4, s3
	v_writelane_b32 v250, s3, 16
	s_mul_hi_u32 s3, s0, s3
	s_mul_i32 s4, s3, s36
	s_sub_i32 s0, s0, s4
	s_add_i32 s5, s3, 1
	s_sub_i32 s4, s0, s36
	s_cmp_ge_u32 s0, s36
	s_cselect_b32 s3, s5, s3
	s_cselect_b32 s0, s4, s0
	s_add_i32 s4, s3, 1
	s_cmp_ge_u32 s0, s36
	s_cselect_b32 s0, s4, s3
	s_xor_b32 s0, s0, s1
	s_not_b32 s1, s1
	s_add_i32 s0, s1, s0
	s_mul_i32 s0, s0, s94
	s_sub_i32 s0, 0x1b0, s0
	s_cmp_lt_i32 s0, s94
	s_cselect_b32 s97, s0, 0
	s_cmp_ge_i32 s2, s97
	s_cselect_b64 s[0:1], -1, 0
	v_writelane_b32 v250, s0, 17
	s_cmp_lt_i32 s2, s97
	s_nop 0
	v_writelane_b32 v250, s1, 18
	v_readfirstlane_b32 s0, v2
	s_cbranch_scc1 .LBB0_317
	s_sub_i32 s1, s2, s97
	s_ashr_i32 s0, s0, 6
	s_lshl_b32 s1, s1, 3
	s_add_i32 s4, s1, s0
	s_movk_i32 s99, 0x1080
	s_cmpk_lg_i32 s94, 0x100
	s_cbranch_scc1 .Ltr1_keep
	s_movk_i32 s99, 0xb00
.Ltr1_keep:
	s_cmpk_gt_i32 s4, 0x127f
	s_cbranch_scc1 .LBB0_317
	s_sub_i32 s1, s94, s97
	s_lshl_b32 s0, s0, 14
	s_lshl_b32 s5, s1, 3
	s_add_i32 s0, s0, 0
	s_add_u32 s10, s34, 0x2200000
	s_addc_u32 s11, s35, 0
	v_bfe_u32 v1, v2, 5, 1
	v_and_b32_e32 v4, 31, v2
	v_bfe_u32 v7, v2, 3, 3
	v_lshlrev_b32_e32 v2, 3, v2
	s_add_u32 s14, s34, 0xc00000
	v_lshlrev_b32_e32 v5, 2, v4
	v_mul_u32_u24_e32 v6, 0x84, v1
	v_and_b32_e32 v20, 56, v2
	s_addc_u32 s15, s35, 0
	v_add3_u32 v6, s0, v5, v6
	v_mul_u32_u24_e32 v2, 0x84, v20
	v_lshlrev_b32_e32 v5, 2, v7
	s_add_u32 s19, s34, 0x800000
	s_waitcnt lgkmcnt(0)
	v_mov_b32_e32 v3, 0
	v_add3_u32 v8, s0, v2, v5
	v_or_b32_e32 v9, 8, v7
	v_or_b32_e32 v10, 16, v7
	v_or_b32_e32 v11, 24, v7
	s_addc_u32 s22, s35, 0
	s_movk_i32 s23, 0x7fff
	s_mov_b32 s26, 0xffff0000
	s_movk_i32 s27, 0x1600
	s_movk_i32 s33, 0x2c00
	v_lshlrev_b32_e32 v2, 2, v4
	v_add_u32_e32 v12, 0x400, v6
	v_add_u32_e32 v13, 0x800, v6
	v_add_u32_e32 v14, 0xc00, v6
	v_add_u32_e32 v15, 0x1000, v6
	v_add_u32_e32 v16, 0x1400, v6
	v_add_u32_e32 v17, 0x1800, v6
	v_add_u32_e32 v18, 0x1c00, v6
	v_lshlrev_b32_e32 v4, 1, v20
	s_branch .LBB0_304

.LBB0_304:
	s_cmp_lt_i32 s4, s99
	s_cbranch_scc1 .Ltr1_do
	s_cmpk_lt_i32 s4, 0x1080
	s_cbranch_scc1 .LBB0_303

.LBB0_568:
	s_cmpk_lg_i32 s94, 0x100
	s_cbranch_scc1 .Ltr1_done
	s_and_b32 s0, s2, 7
	s_cmp_lt_u32 s0, 2
	s_cbranch_scc1 .Ltr1_done
	v_mov_b32_e32 v2, v0
	s_nop 0
	v_readfirstlane_b32 s0, v2
	s_and_b32 s1, s2, 7
	s_add_i32 s1, s1, -2
	s_lshl_b32 s1, s1, 5
	s_lshr_b32 s3, s2, 3
	s_add_i32 s1, s1, s3
	s_ashr_i32 s0, s0, 6
	s_lshl_b32 s1, s1, 3
	s_add_i32 s4, s1, s0
	s_addk_i32 s4, 0xb00
	s_cmpk_gt_i32 s4, 0x107f
	s_cbranch_scc1 .Ltr1_done
	s_movk_i32 s1, 0xc0
	s_lshl_b32 s0, s0, 14
	s_lshl_b32 s5, s1, 3
	s_add_i32 s0, s0, 0
	s_add_u32 s10, s34, 0x2200000
	s_addc_u32 s11, s35, 0
	v_bfe_u32 v1, v2, 5, 1
	v_and_b32_e32 v4, 31, v2
	v_bfe_u32 v7, v2, 3, 3
	v_lshlrev_b32_e32 v2, 3, v2
	s_add_u32 s14, s34, 0xc00000
	v_lshlrev_b32_e32 v5, 2, v4
	v_mul_u32_u24_e32 v6, 0x84, v1
	v_and_b32_e32 v20, 56, v2
	s_addc_u32 s15, s35, 0
	v_add3_u32 v6, s0, v5, v6
	v_mul_u32_u24_e32 v2, 0x84, v20
	v_lshlrev_b32_e32 v5, 2, v7
	s_add_u32 s19, s34, 0x800000
	s_waitcnt lgkmcnt(0)
	v_mov_b32_e32 v3, 0
	v_add3_u32 v8, s0, v2, v5
	v_or_b32_e32 v9, 8, v7
	v_or_b32_e32 v10, 16, v7
	v_or_b32_e32 v11, 24, v7
	s_addc_u32 s22, s35, 0
	s_movk_i32 s23, 0x7fff
	s_mov_b32 s101, 0xffff0000
	s_movk_i32 s27, 0x1600
	s_movk_i32 s33, 0x2c00
	v_lshlrev_b32_e32 v2, 2, v4
	v_add_u32_e32 v12, 0x400, v6
	v_add_u32_e32 v13, 0x800, v6
	v_add_u32_e32 v14, 0xc00, v6
	v_add_u32_e32 v15, 0x1000, v6
	v_add_u32_e32 v16, 0x1400, v6
	v_add_u32_e32 v17, 0x1800, v6
	v_add_u32_e32 v18, 0x1c00, v6
	v_lshlrev_b32_e32 v4, 1, v20
	s_branch .Ltr1_304
.Ltr1_303:
	s_add_i32 s4, s4, s5
	s_cmpk_lt_i32 s4, 0x1080
	s_cbranch_scc0 .Ltr1_done

.Ltr1_311:
	s_and_b64 vcc, exec, s[0:1]
	s_mul_i32 s9, s8, 0xb00000
	s_cbranch_vccz .Ltr1_313
	s_ashr_i32 s0, s12, 31
	s_lshr_b32 s0, s0, 27
	s_add_i32 s0, s12, s0
	s_and_b32 s1, s0, 0x7ffffe0
	s_sub_i32 s1, s12, s1
	s_add_u32 s3, s58, s9
	s_addc_u32 s7, s59, 0
	s_mul_i32 s6, s8, 0x580000
	s_add_u32 s37, s10, s6
	s_addc_u32 s13, s11, 0
	s_lshl_b32 s0, s0, 1
	s_and_b32 s6, s0, 0xffffffc0
	s_lshl_b32 s0, s1, 5
	s_ashr_i32 s1, s0, 31
	v_or_b32_e32 v20, s6, v1
	s_lshl_b64 s[24:25], s[0:1], 2
	s_add_u32 s24, s3, s24
	v_or_b32_e32 v26, 2, v20
	v_or_b32_e32 v28, 4, v20
	v_or_b32_e32 v30, 6, v20
	v_or_b32_e32 v32, 8, v20
	v_or_b32_e32 v34, 10, v20
	v_or_b32_e32 v36, 12, v20
	v_or_b32_e32 v38, 14, v20
	s_addc_u32 s25, s7, s25
	v_ashrrev_i32_e32 v21, 31, v20
	v_ashrrev_i32_e32 v27, 31, v26
	v_ashrrev_i32_e32 v29, 31, v28
	v_ashrrev_i32_e32 v31, 31, v30
	v_ashrrev_i32_e32 v33, 31, v32
	v_ashrrev_i32_e32 v35, 31, v34
	v_ashrrev_i32_e32 v37, 31, v36
	v_ashrrev_i32_e32 v39, 31, v38
	v_lshl_add_u64 v[22:23], s[24:25], 0, v[2:3]
	v_lshlrev_b64 v[24:25], 12, v[20:21]
	v_lshlrev_b64 v[26:27], 12, v[26:27]
	v_lshlrev_b64 v[28:29], 12, v[28:29]
	v_lshlrev_b64 v[30:31], 12, v[30:31]
	v_lshlrev_b64 v[32:33], 12, v[32:33]
	v_lshlrev_b64 v[34:35], 12, v[34:35]
	v_lshlrev_b64 v[36:37], 12, v[36:37]
	v_lshlrev_b64 v[38:39], 12, v[38:39]
	v_lshl_add_u64 v[24:25], v[22:23], 0, v[24:25]
	v_lshl_add_u64 v[26:27], v[22:23], 0, v[26:27]
	v_lshl_add_u64 v[28:29], v[22:23], 0, v[28:29]
	v_lshl_add_u64 v[30:31], v[22:23], 0, v[30:31]
	v_lshl_add_u64 v[32:33], v[22:23], 0, v[32:33]
	v_lshl_add_u64 v[34:35], v[22:23], 0, v[34:35]
	v_lshl_add_u64 v[36:37], v[22:23], 0, v[36:37]
	v_lshl_add_u64 v[38:39], v[22:23], 0, v[38:39]
	global_load_dword v5, v[24:25], off nt
	global_load_dword v19, v[26:27], off nt
	global_load_dword v40, v[28:29], off nt
	global_load_dword v41, v[30:31], off nt
	global_load_dword v42, v[32:33], off nt
	global_load_dword v43, v[34:35], off nt
	global_load_dword v44, v[36:37], off nt
	global_load_dword v45, v[38:39], off nt
	v_or_b32_e32 v24, 16, v20
	v_or_b32_e32 v26, 18, v20
	v_or_b32_e32 v28, 20, v20
	v_or_b32_e32 v30, 22, v20
	v_or_b32_e32 v32, 24, v20
	v_or_b32_e32 v34, 26, v20
	v_or_b32_e32 v36, 28, v20
	v_or_b32_e32 v38, 30, v20
	v_ashrrev_i32_e32 v25, 31, v24
	v_ashrrev_i32_e32 v27, 31, v26
	v_ashrrev_i32_e32 v29, 31, v28
	v_ashrrev_i32_e32 v31, 31, v30
	v_ashrrev_i32_e32 v33, 31, v32
	v_ashrrev_i32_e32 v35, 31, v34
	v_ashrrev_i32_e32 v37, 31, v36
	v_ashrrev_i32_e32 v39, 31, v38
	v_lshlrev_b64 v[24:25], 12, v[24:25]
	v_lshlrev_b64 v[26:27], 12, v[26:27]
	v_lshlrev_b64 v[28:29], 12, v[28:29]
	v_lshlrev_b64 v[30:31], 12, v[30:31]
	v_lshlrev_b64 v[32:33], 12, v[32:33]
	v_lshlrev_b64 v[34:35], 12, v[34:35]
	v_lshlrev_b64 v[36:37], 12, v[36:37]
	v_lshlrev_b64 v[38:39], 12, v[38:39]
	v_lshl_add_u64 v[24:25], v[22:23], 0, v[24:25]
	v_lshl_add_u64 v[26:27], v[22:23], 0, v[26:27]
	v_lshl_add_u64 v[28:29], v[22:23], 0, v[28:29]
	v_lshl_add_u64 v[30:31], v[22:23], 0, v[30:31]
	v_lshl_add_u64 v[32:33], v[22:23], 0, v[32:33]
	v_lshl_add_u64 v[34:35], v[22:23], 0, v[34:35]
	v_lshl_add_u64 v[36:37], v[22:23], 0, v[36:37]
	v_lshl_add_u64 v[38:39], v[22:23], 0, v[38:39]
	global_load_dword v46, v[24:25], off nt
	global_load_dword v47, v[26:27], off nt
	global_load_dword v48, v[28:29], off nt
	global_load_dword v49, v[30:31], off nt
	global_load_dword v50, v[32:33], off nt
	global_load_dword v51, v[34:35], off nt
	global_load_dword v52, v[36:37], off nt
	global_load_dword v53, v[38:39], off nt
	v_or_b32_e32 v24, 32, v20
	v_or_b32_e32 v26, 34, v20
	v_or_b32_e32 v28, 36, v20
	v_or_b32_e32 v30, 38, v20
	v_or_b32_e32 v32, 40, v20
	v_or_b32_e32 v34, 42, v20
	v_or_b32_e32 v36, 44, v20
	v_or_b32_e32 v38, 46, v20
	v_ashrrev_i32_e32 v25, 31, v24
	v_ashrrev_i32_e32 v27, 31, v26
	v_ashrrev_i32_e32 v29, 31, v28
	v_ashrrev_i32_e32 v31, 31, v30
	v_ashrrev_i32_e32 v33, 31, v32
	v_ashrrev_i32_e32 v35, 31, v34
	v_ashrrev_i32_e32 v37, 31, v36
	v_ashrrev_i32_e32 v39, 31, v38
	v_lshlrev_b64 v[24:25], 12, v[24:25]
	v_lshlrev_b64 v[26:27], 12, v[26:27]
	v_lshlrev_b64 v[28:29], 12, v[28:29]
	v_lshlrev_b64 v[30:31], 12, v[30:31]
	v_lshlrev_b64 v[32:33], 12, v[32:33]
	v_lshlrev_b64 v[34:35], 12, v[34:35]
	v_lshlrev_b64 v[36:37], 12, v[36:37]
	v_lshlrev_b64 v[38:39], 12, v[38:39]
	v_lshl_add_u64 v[24:25], v[22:23], 0, v[24:25]
	v_lshl_add_u64 v[26:27], v[22:23], 0, v[26:27]
	v_lshl_add_u64 v[28:29], v[22:23], 0, v[28:29]
	v_lshl_add_u64 v[30:31], v[22:23], 0, v[30:31]
	v_lshl_add_u64 v[32:33], v[22:23], 0, v[32:33]
	v_lshl_add_u64 v[34:35], v[22:23], 0, v[34:35]
	v_lshl_add_u64 v[36:37], v[22:23], 0, v[36:37]
	v_lshl_add_u64 v[38:39], v[22:23], 0, v[38:39]
	global_load_dword v54, v[24:25], off nt
	global_load_dword v55, v[26:27], off nt
	global_load_dword v56, v[28:29], off nt
	global_load_dword v57, v[30:31], off nt
	global_load_dword v58, v[32:33], off nt
	global_load_dword v59, v[34:35], off nt
	global_load_dword v60, v[36:37], off nt
	s_nop 0
	global_load_dword v38, v[38:39], off nt
	v_or_b32_e32 v24, 48, v20
	v_or_b32_e32 v26, 50, v20
	v_or_b32_e32 v28, 52, v20
	v_or_b32_e32 v30, 54, v20
	v_or_b32_e32 v32, 56, v20
	v_or_b32_e32 v34, 58, v20
	v_or_b32_e32 v36, 60, v20
	v_or_b32_e32 v20, 62, v20
	v_ashrrev_i32_e32 v25, 31, v24
	v_ashrrev_i32_e32 v27, 31, v26
	v_ashrrev_i32_e32 v29, 31, v28
	v_ashrrev_i32_e32 v21, 31, v20
	v_lshlrev_b64 v[24:25], 12, v[24:25]
	v_lshlrev_b64 v[26:27], 12, v[26:27]
	v_lshlrev_b64 v[28:29], 12, v[28:29]
	v_ashrrev_i32_e32 v31, 31, v30
	v_ashrrev_i32_e32 v33, 31, v32
	v_ashrrev_i32_e32 v35, 31, v34
	v_ashrrev_i32_e32 v37, 31, v36
	v_lshlrev_b64 v[20:21], 12, v[20:21]
	v_lshl_add_u64 v[24:25], v[22:23], 0, v[24:25]
	v_lshl_add_u64 v[26:27], v[22:23], 0, v[26:27]
	v_lshl_add_u64 v[28:29], v[22:23], 0, v[28:29]
	v_lshlrev_b64 v[30:31], 12, v[30:31]
	v_lshlrev_b64 v[32:33], 12, v[32:33]
	v_lshlrev_b64 v[34:35], 12, v[34:35]
	v_lshlrev_b64 v[36:37], 12, v[36:37]
	v_lshl_add_u64 v[20:21], v[22:23], 0, v[20:21]
	v_lshl_add_u64 v[30:31], v[22:23], 0, v[30:31]
	v_lshl_add_u64 v[32:33], v[22:23], 0, v[32:33]
	v_lshl_add_u64 v[34:35], v[22:23], 0, v[34:35]
	v_lshl_add_u64 v[36:37], v[22:23], 0, v[36:37]
	global_load_dword v22, v[24:25], off nt
	global_load_dword v23, v[26:27], off nt
	s_nop 0
	global_load_dword v24, v[28:29], off nt
	global_load_dword v25, v[30:31], off nt
	global_load_dword v26, v[32:33], off nt
	global_load_dword v27, v[34:35], off nt
	s_nop 0
	global_load_dword v28, v[36:37], off nt
	s_nop 0
	global_load_dword v20, v[20:21], off nt
	s_waitcnt vmcnt(0)
	ds_write2_b32 v6, v5, v19 offset1:66
	ds_write2_b32 v6, v40, v41 offset0:132 offset1:198
	ds_write2_b32 v12, v42, v43 offset0:8 offset1:74
	ds_write2_b32 v12, v44, v45 offset0:140 offset1:206
	ds_write2_b32 v13, v46, v47 offset0:16 offset1:82
	ds_write2_b32 v13, v48, v49 offset0:148 offset1:214
	ds_write2_b32 v14, v50, v51 offset0:24 offset1:90
	ds_write2_b32 v14, v52, v53 offset0:156 offset1:222
	ds_write2_b32 v15, v54, v55 offset0:32 offset1:98
	ds_write2_b32 v15, v56, v57 offset0:164 offset1:230
	ds_write2_b32 v16, v58, v59 offset0:40 offset1:106
	ds_write2_b32 v16, v60, v38 offset0:172 offset1:238
	ds_write2_b32 v17, v22, v23 offset0:48 offset1:114
	ds_write2_b32 v17, v24, v25 offset0:180 offset1:246
	ds_write2_b32 v18, v26, v27 offset0:56 offset1:122
	ds_write2_b32 v18, v28, v20 offset0:188 offset1:254
	s_waitcnt lgkmcnt(0)
	ds_read2_b32 v[24:25], v8 offset1:8
	s_ashr_i32 s7, s6, 31
	ds_read2_b32 v[28:29], v8 offset0:33 offset1:41
	s_lshl_b64 s[6:7], s[6:7], 1
	s_add_u32 s6, s37, s6
	ds_read2_b32 v[30:31], v8 offset0:66 offset1:74
	s_addc_u32 s7, s13, s7
	v_mov_b32_e32 v5, v3
	ds_read2_b32 v[32:33], v8 offset0:99 offset1:107
	v_lshl_add_u64 v[26:27], s[6:7], 0, v[4:5]
	s_waitcnt lgkmcnt(3)
	v_bfe_u32 v5, v24, 16, 1
	v_add3_u32 v5, v24, v5, s23
	s_waitcnt lgkmcnt(2)
	v_bfe_u32 v19, v28, 16, 1
	ds_read2_b32 v[34:35], v8 offset0:132 offset1:140
	v_lshrrev_b32_e32 v5, 16, v5
	v_add3_u32 v19, v28, v19, s23
	ds_read2_b32 v[36:37], v8 offset0:165 offset1:173
	v_and_or_b32 v20, v19, s101, v5
	s_waitcnt lgkmcnt(3)
	v_bfe_u32 v5, v30, 16, 1
	v_add3_u32 v5, v30, v5, s23
	s_waitcnt lgkmcnt(2)
	v_bfe_u32 v19, v32, 16, 1
	ds_read2_b32 v[38:39], v8 offset0:198 offset1:206
	v_lshrrev_b32_e32 v5, 16, v5
	v_add3_u32 v19, v32, v19, s23
	ds_read2_b32 v[40:41], v8 offset0:231 offset1:239
	v_and_or_b32 v21, v19, s101, v5
	s_waitcnt lgkmcnt(3)
	v_bfe_u32 v5, v34, 16, 1
	v_add3_u32 v5, v34, v5, s23
	s_waitcnt lgkmcnt(2)
	v_bfe_u32 v19, v36, 16, 1
	v_lshrrev_b32_e32 v5, 16, v5
	v_add3_u32 v19, v36, v19, s23
	v_and_or_b32 v22, v19, s101, v5
	s_waitcnt lgkmcnt(1)
	v_bfe_u32 v5, v38, 16, 1
	v_add3_u32 v5, v38, v5, s23
	s_waitcnt lgkmcnt(0)
	v_bfe_u32 v19, v40, 16, 1
	v_lshrrev_b32_e32 v5, 16, v5
	v_add3_u32 v19, v40, v19, s23
	v_and_or_b32 v23, v19, s101, v5
	v_or_b32_e32 v5, s0, v7
	v_mul_lo_u32 v42, v5, s27
	v_bfe_u32 v5, v25, 16, 1
	v_ashrrev_i32_e32 v43, 31, v42
	v_add3_u32 v5, v25, v5, s23
	v_bfe_u32 v19, v29, 16, 1
	v_lshl_add_u64 v[42:43], v[26:27], 0, v[42:43]
	v_lshrrev_b32_e32 v5, 16, v5
	v_add3_u32 v19, v29, v19, s23
	global_store_dwordx4 v[42:43], v[20:23], off
	ds_read2_b32 v[28:29], v8 offset0:16 offset1:24
	s_mov_b64 s[6:7], 0
	v_and_or_b32 v20, v19, s101, v5
	v_bfe_u32 v5, v31, 16, 1
	v_add3_u32 v5, v31, v5, s23
	v_bfe_u32 v19, v33, 16, 1
	v_lshrrev_b32_e32 v5, 16, v5
	v_add3_u32 v19, v33, v19, s23
	v_and_or_b32 v21, v19, s101, v5
	v_bfe_u32 v5, v35, 16, 1
	v_add3_u32 v5, v35, v5, s23
	v_bfe_u32 v19, v37, 16, 1
	v_lshrrev_b32_e32 v5, 16, v5
	v_add3_u32 v19, v37, v19, s23
	v_and_or_b32 v22, v19, s101, v5
	v_bfe_u32 v5, v39, 16, 1
	v_add3_u32 v5, v39, v5, s23
	v_bfe_u32 v19, v41, 16, 1
	v_lshrrev_b32_e32 v5, 16, v5
	v_add3_u32 v19, v41, v19, s23
	v_and_or_b32 v23, v19, s101, v5
	v_or_b32_e32 v5, s0, v9
	v_mul_lo_u32 v24, v5, s27
	v_ashrrev_i32_e32 v25, 31, v24
	v_lshl_add_u64 v[24:25], v[26:27], 0, v[24:25]
	global_store_dwordx4 v[24:25], v[20:23], off
	ds_read2_b32 v[24:25], v8 offset0:49 offset1:57
	ds_read2_b32 v[30:31], v8 offset0:82 offset1:90
	ds_read2_b32 v[32:33], v8 offset0:115 offset1:123
	s_waitcnt lgkmcnt(3)
	v_bfe_u32 v5, v28, 16, 1
	v_add3_u32 v5, v28, v5, s23
	s_waitcnt lgkmcnt(2)
	v_bfe_u32 v19, v24, 16, 1
	ds_read2_b32 v[34:35], v8 offset0:148 offset1:156
	v_lshrrev_b32_e32 v5, 16, v5
	v_add3_u32 v19, v24, v19, s23
	ds_read2_b32 v[36:37], v8 offset0:181 offset1:189
	v_and_or_b32 v20, v19, s101, v5
	s_waitcnt lgkmcnt(3)
	v_bfe_u32 v5, v30, 16, 1
	v_add3_u32 v5, v30, v5, s23
	s_waitcnt lgkmcnt(2)
	v_bfe_u32 v19, v32, 16, 1
	ds_read2_b32 v[38:39], v8 offset0:214 offset1:222
	v_lshrrev_b32_e32 v5, 16, v5
	v_add3_u32 v19, v32, v19, s23
	ds_read2_b32 v[40:41], v8 offset0:247 offset1:255
	v_and_or_b32 v21, v19, s101, v5
	s_waitcnt lgkmcnt(3)
	v_bfe_u32 v5, v34, 16, 1
	v_add3_u32 v5, v34, v5, s23
	s_waitcnt lgkmcnt(2)
	v_bfe_u32 v19, v36, 16, 1
	v_lshrrev_b32_e32 v5, 16, v5
	v_add3_u32 v19, v36, v19, s23
	v_and_or_b32 v22, v19, s101, v5
	s_waitcnt lgkmcnt(1)
	v_bfe_u32 v5, v38, 16, 1
	v_add3_u32 v5, v38, v5, s23
	s_waitcnt lgkmcnt(0)
	v_bfe_u32 v19, v40, 16, 1
	v_lshrrev_b32_e32 v5, 16, v5
	v_add3_u32 v19, v40, v19, s23
	v_and_or_b32 v23, v19, s101, v5
	v_or_b32_e32 v5, s0, v10
	v_mul_lo_u32 v42, v5, s27
	v_bfe_u32 v5, v29, 16, 1
	v_ashrrev_i32_e32 v43, 31, v42
	v_add3_u32 v5, v29, v5, s23
	v_bfe_u32 v19, v25, 16, 1
	v_lshl_add_u64 v[42:43], v[26:27], 0, v[42:43]
	v_lshrrev_b32_e32 v5, 16, v5
	v_add3_u32 v19, v25, v19, s23
	global_store_dwordx4 v[42:43], v[20:23], off
	s_nop 1
	v_and_or_b32 v20, v19, s101, v5
	v_bfe_u32 v5, v31, 16, 1
	v_add3_u32 v5, v31, v5, s23
	v_bfe_u32 v19, v33, 16, 1
	v_lshrrev_b32_e32 v5, 16, v5
	v_add3_u32 v19, v33, v19, s23
	v_and_or_b32 v21, v19, s101, v5
	v_bfe_u32 v5, v35, 16, 1
	v_add3_u32 v5, v35, v5, s23
	v_bfe_u32 v19, v37, 16, 1
	v_lshrrev_b32_e32 v5, 16, v5
	v_add3_u32 v19, v37, v19, s23
	v_and_or_b32 v22, v19, s101, v5
	v_bfe_u32 v5, v39, 16, 1
	v_add3_u32 v5, v39, v5, s23
	v_bfe_u32 v19, v41, 16, 1
	v_lshrrev_b32_e32 v5, 16, v5
	v_add3_u32 v19, v41, v19, s23
	v_and_or_b32 v23, v19, s101, v5
	v_or_b32_e32 v5, s0, v11
	v_mul_lo_u32 v24, v5, s27
	v_ashrrev_i32_e32 v25, 31, v24
	v_lshl_add_u64 v[24:25], v[26:27], 0, v[24:25]
	global_store_dwordx4 v[24:25], v[20:23], off
	s_waitcnt lgkmcnt(0)
.Ltr1_313:
	s_andn2_b64 vcc, exec, s[6:7]
	s_cbranch_vccnz .Ltr1_315
	s_add_i32 s0, s12, 0xfffffa80
	s_cmpk_gt_i32 s12, 0x57f
	s_cselect_b32 s0, s0, s12
	s_mul_hi_i32 s3, s0, 0x2e8ba2e9
	s_cselect_b32 s1, 0x80, 0
	s_cselect_b32 s6, s57, s55
	s_cselect_b32 s7, s56, s54
	s_lshr_b32 s13, s3, 31
	s_ashr_i32 s3, s3, 4
	s_add_i32 s3, s3, s13
	s_mul_i32 s13, s3, 0x58
	s_sub_i32 s13, s0, s13
	s_lshl_b32 s24, s13, 5
	s_add_u32 s7, s7, s9
	s_addc_u32 s37, s6, 0
	s_add_u32 s9, s14, s9
	s_addc_u32 s44, s15, 0
	s_lshl_b32 s0, s3, 6
	s_lshl_b32 s3, s13, 6
	s_and_b32 s6, s24, 0x60
	s_and_b32 s3, s3, 0xffffff00
	s_or_b32 s1, s6, s1
	s_ashr_i32 s25, s24, 31
	s_or_b32 s6, s1, s3
	s_lshl_b64 s[24:25], s[24:25], 2
	s_add_u32 s24, s7, s24
	v_or_b32_e32 v5, s0, v1
	s_addc_u32 s25, s37, s25
	v_lshl_add_u64 v[20:21], s[24:25], 0, v[2:3]
	v_or_b32_e32 v19, 2, v5
	v_mad_i64_i32 v[24:25], s[24:25], v19, s33, v[20:21]
	v_or_b32_e32 v19, 4, v5
	v_mad_i64_i32 v[26:27], s[24:25], v19, s33, v[20:21]
	v_or_b32_e32 v19, 6, v5
	v_mad_i64_i32 v[28:29], s[24:25], v19, s33, v[20:21]
	v_or_b32_e32 v19, 8, v5
	v_mad_i64_i32 v[30:31], s[24:25], v19, s33, v[20:21]
	v_or_b32_e32 v19, 10, v5
	v_mad_i64_i32 v[32:33], s[24:25], v19, s33, v[20:21]
	v_or_b32_e32 v19, 12, v5
	v_mad_i64_i32 v[34:35], s[24:25], v19, s33, v[20:21]
	v_or_b32_e32 v19, 14, v5
	v_mad_i64_i32 v[22:23], s[24:25], v5, s33, v[20:21]
	v_mad_i64_i32 v[36:37], s[24:25], v19, s33, v[20:21]
	global_load_dword v19, v[22:23], off nt
	global_load_dword v38, v[24:25], off nt
	global_load_dword v39, v[26:27], off nt
	global_load_dword v40, v[28:29], off nt
	global_load_dword v41, v[30:31], off nt
	global_load_dword v42, v[32:33], off nt
	global_load_dword v43, v[34:35], off nt
	global_load_dword v44, v[36:37], off nt
	v_or_b32_e32 v22, 16, v5
	v_or_b32_e32 v24, 18, v5
	v_or_b32_e32 v26, 20, v5
	v_or_b32_e32 v28, 22, v5
	v_or_b32_e32 v30, 24, v5
	v_or_b32_e32 v32, 26, v5
	v_or_b32_e32 v34, 28, v5
	v_or_b32_e32 v36, 30, v5
	v_mad_i64_i32 v[22:23], s[24:25], v22, s33, v[20:21]
	v_mad_i64_i32 v[24:25], s[24:25], v24, s33, v[20:21]
	v_mad_i64_i32 v[26:27], s[24:25], v26, s33, v[20:21]
	v_mad_i64_i32 v[28:29], s[24:25], v28, s33, v[20:21]
	v_mad_i64_i32 v[30:31], s[24:25], v30, s33, v[20:21]
	v_mad_i64_i32 v[32:33], s[24:25], v32, s33, v[20:21]
	v_mad_i64_i32 v[34:35], s[24:25], v34, s33, v[20:21]
	v_mad_i64_i32 v[36:37], s[24:25], v36, s33, v[20:21]
	global_load_dword v45, v[22:23], off nt
	global_load_dword v46, v[24:25], off nt
	global_load_dword v47, v[26:27], off nt
	global_load_dword v48, v[28:29], off nt
	global_load_dword v49, v[30:31], off nt
	global_load_dword v50, v[32:33], off nt
	global_load_dword v51, v[34:35], off nt
	global_load_dword v52, v[36:37], off nt
	v_or_b32_e32 v22, 32, v5
	v_or_b32_e32 v24, 34, v5
	v_or_b32_e32 v26, 36, v5
	v_or_b32_e32 v28, 38, v5
	v_or_b32_e32 v30, 40, v5
	v_or_b32_e32 v32, 42, v5
	v_or_b32_e32 v34, 44, v5
	v_or_b32_e32 v36, 46, v5
	v_mad_i64_i32 v[22:23], s[24:25], v22, s33, v[20:21]
	v_mad_i64_i32 v[24:25], s[24:25], v24, s33, v[20:21]
	v_mad_i64_i32 v[26:27], s[24:25], v26, s33, v[20:21]
	v_mad_i64_i32 v[28:29], s[24:25], v28, s33, v[20:21]
	v_mad_i64_i32 v[30:31], s[24:25], v30, s33, v[20:21]
	v_mad_i64_i32 v[32:33], s[24:25], v32, s33, v[20:21]
	v_mad_i64_i32 v[34:35], s[24:25], v34, s33, v[20:21]
	v_mad_i64_i32 v[36:37], s[24:25], v36, s33, v[20:21]
	global_load_dword v53, v[22:23], off nt
	global_load_dword v54, v[24:25], off nt
	global_load_dword v55, v[26:27], off nt
	global_load_dword v56, v[28:29], off nt
	global_load_dword v57, v[30:31], off nt
	global_load_dword v58, v[32:33], off nt
	global_load_dword v59, v[34:35], off nt
	s_nop 0
	global_load_dword v36, v[36:37], off nt
	v_or_b32_e32 v22, 48, v5
	v_or_b32_e32 v24, 50, v5
	v_or_b32_e32 v26, 52, v5
	v_or_b32_e32 v28, 54, v5
	v_or_b32_e32 v30, 56, v5
	v_or_b32_e32 v32, 58, v5
	v_or_b32_e32 v34, 60, v5
	v_or_b32_e32 v5, 62, v5
	v_mad_i64_i32 v[22:23], s[24:25], v22, s33, v[20:21]
	v_mad_i64_i32 v[24:25], s[24:25], v24, s33, v[20:21]
	v_mad_i64_i32 v[26:27], s[24:25], v26, s33, v[20:21]
	v_mad_i64_i32 v[28:29], s[24:25], v28, s33, v[20:21]
	v_mad_i64_i32 v[30:31], s[24:25], v30, s33, v[20:21]
	v_mad_i64_i32 v[32:33], s[24:25], v32, s33, v[20:21]
	v_mad_i64_i32 v[34:35], s[24:25], v34, s33, v[20:21]
	v_mad_i64_i32 v[20:21], s[24:25], v5, s33, v[20:21]
	global_load_dword v5, v[22:23], off nt
	s_nop 0
	global_load_dword v22, v[24:25], off nt
	global_load_dword v23, v[26:27], off nt
	s_nop 0
	global_load_dword v24, v[28:29], off nt
	global_load_dword v25, v[30:31], off nt
	global_load_dword v26, v[32:33], off nt
	global_load_dword v27, v[34:35], off nt
	s_nop 0
	global_load_dword v20, v[20:21], off nt
	s_waitcnt vmcnt(0)
	ds_write2_b32 v6, v19, v38 offset1:66
	ds_write2_b32 v6, v39, v40 offset0:132 offset1:198
	ds_write2_b32 v12, v41, v42 offset0:8 offset1:74
	ds_write2_b32 v12, v43, v44 offset0:140 offset1:206
	ds_write2_b32 v13, v45, v46 offset0:16 offset1:82
	ds_write2_b32 v13, v47, v48 offset0:148 offset1:214
	ds_write2_b32 v14, v49, v50 offset0:24 offset1:90
	ds_write2_b32 v14, v51, v52 offset0:156 offset1:222
	ds_write2_b32 v15, v53, v54 offset0:32 offset1:98
	ds_write2_b32 v15, v55, v56 offset0:164 offset1:230
	ds_write2_b32 v16, v57, v58 offset0:40 offset1:106
	ds_write2_b32 v16, v59, v36 offset0:172 offset1:238
	ds_write2_b32 v17, v5, v22 offset0:48 offset1:114
	ds_write2_b32 v17, v23, v24 offset0:180 offset1:246
	ds_write2_b32 v18, v25, v26 offset0:56 offset1:122
	ds_write2_b32 v18, v27, v20 offset0:188 offset1:254
	s_waitcnt lgkmcnt(0)
	ds_read2_b32 v[24:25], v8 offset1:8
	s_ashr_i32 s1, s0, 31
	ds_read2_b32 v[28:29], v8 offset0:33 offset1:41
	s_lshl_b64 s[0:1], s[0:1], 1
	s_add_u32 s0, s9, s0
	ds_read2_b32 v[30:31], v8 offset0:66 offset1:74
	s_addc_u32 s1, s44, s1
	v_mov_b32_e32 v5, v3
	ds_read2_b32 v[32:33], v8 offset0:99 offset1:107
	v_lshl_add_u64 v[26:27], s[0:1], 0, v[4:5]
	s_waitcnt lgkmcnt(3)
	v_bfe_u32 v5, v24, 16, 1
	v_add3_u32 v5, v24, v5, s23
	s_waitcnt lgkmcnt(2)
	v_bfe_u32 v19, v28, 16, 1
	ds_read2_b32 v[34:35], v8 offset0:132 offset1:140
	v_lshrrev_b32_e32 v5, 16, v5
	v_add3_u32 v19, v28, v19, s23
	ds_read2_b32 v[36:37], v8 offset0:165 offset1:173
	v_and_or_b32 v20, v19, s101, v5
	s_waitcnt lgkmcnt(3)
	v_bfe_u32 v5, v30, 16, 1
	v_add3_u32 v5, v30, v5, s23
	s_waitcnt lgkmcnt(2)
	v_bfe_u32 v19, v32, 16, 1
	ds_read2_b32 v[38:39], v8 offset0:198 offset1:206
	v_lshrrev_b32_e32 v5, 16, v5
	v_add3_u32 v19, v32, v19, s23
	ds_read2_b32 v[40:41], v8 offset0:231 offset1:239
	v_and_or_b32 v21, v19, s101, v5
	s_waitcnt lgkmcnt(3)
	v_bfe_u32 v5, v34, 16, 1
	v_add3_u32 v5, v34, v5, s23
	s_waitcnt lgkmcnt(2)
	v_bfe_u32 v19, v36, 16, 1
	v_lshrrev_b32_e32 v5, 16, v5
	v_add3_u32 v19, v36, v19, s23
	v_and_or_b32 v22, v19, s101, v5
	s_waitcnt lgkmcnt(1)
	v_bfe_u32 v5, v38, 16, 1
	v_add3_u32 v5, v38, v5, s23
	s_waitcnt lgkmcnt(0)
	v_bfe_u32 v19, v40, 16, 1
	v_lshrrev_b32_e32 v5, 16, v5
	v_add3_u32 v19, v40, v19, s23
	v_or_b32_e32 v42, s6, v7
	v_and_or_b32 v23, v19, s101, v5
	v_ashrrev_i32_e32 v43, 31, v42
	v_bfe_u32 v5, v25, 16, 1
	v_lshlrev_b64 v[42:43], 11, v[42:43]
	v_add3_u32 v5, v25, v5, s23
	v_bfe_u32 v19, v29, 16, 1
	v_lshl_add_u64 v[42:43], v[26:27], 0, v[42:43]
	v_lshrrev_b32_e32 v5, 16, v5
	v_add3_u32 v19, v29, v19, s23
	global_store_dwordx4 v[42:43], v[20:23], off
	v_or_b32_e32 v24, s6, v9
	v_ashrrev_i32_e32 v25, 31, v24
	v_and_or_b32 v20, v19, s101, v5
	v_bfe_u32 v5, v31, 16, 1
	v_add3_u32 v5, v31, v5, s23
	v_bfe_u32 v19, v33, 16, 1
	v_lshrrev_b32_e32 v5, 16, v5
	v_add3_u32 v19, v33, v19, s23
	v_and_or_b32 v21, v19, s101, v5
	v_bfe_u32 v5, v35, 16, 1
	v_add3_u32 v5, v35, v5, s23
	v_bfe_u32 v19, v37, 16, 1
	v_lshrrev_b32_e32 v5, 16, v5
	v_add3_u32 v19, v37, v19, s23
	v_and_or_b32 v22, v19, s101, v5
	v_bfe_u32 v5, v39, 16, 1
	v_add3_u32 v5, v39, v5, s23
	v_bfe_u32 v19, v41, 16, 1
	v_lshrrev_b32_e32 v5, 16, v5
	v_add3_u32 v19, v41, v19, s23
	v_lshlrev_b64 v[24:25], 11, v[24:25]
	v_and_or_b32 v23, v19, s101, v5
	ds_read2_b32 v[28:29], v8 offset0:16 offset1:24
	v_lshl_add_u64 v[24:25], v[26:27], 0, v[24:25]
	global_store_dwordx4 v[24:25], v[20:23], off
	ds_read2_b32 v[24:25], v8 offset0:49 offset1:57
	ds_read2_b32 v[30:31], v8 offset0:82 offset1:90
	ds_read2_b32 v[32:33], v8 offset0:115 offset1:123
	s_waitcnt lgkmcnt(3)
	v_bfe_u32 v5, v28, 16, 1
	v_add3_u32 v5, v28, v5, s23
	s_waitcnt lgkmcnt(2)
	v_bfe_u32 v19, v24, 16, 1
	ds_read2_b32 v[34:35], v8 offset0:148 offset1:156
	v_lshrrev_b32_e32 v5, 16, v5
	v_add3_u32 v19, v24, v19, s23
	ds_read2_b32 v[36:37], v8 offset0:181 offset1:189
	v_and_or_b32 v20, v19, s101, v5
	s_waitcnt lgkmcnt(3)
	v_bfe_u32 v5, v30, 16, 1
	v_add3_u32 v5, v30, v5, s23
	s_waitcnt lgkmcnt(2)
	v_bfe_u32 v19, v32, 16, 1
	ds_read2_b32 v[38:39], v8 offset0:214 offset1:222
	v_lshrrev_b32_e32 v5, 16, v5
	v_add3_u32 v19, v32, v19, s23
	ds_read2_b32 v[40:41], v8 offset0:247 offset1:255
	v_and_or_b32 v21, v19, s101, v5
	s_waitcnt lgkmcnt(3)
	v_bfe_u32 v5, v34, 16, 1
	v_add3_u32 v5, v34, v5, s23
	s_waitcnt lgkmcnt(2)
	v_bfe_u32 v19, v36, 16, 1
	v_lshrrev_b32_e32 v5, 16, v5
	v_add3_u32 v19, v36, v19, s23
	v_and_or_b32 v22, v19, s101, v5
	s_waitcnt lgkmcnt(1)
	v_bfe_u32 v5, v38, 16, 1
	v_add3_u32 v5, v38, v5, s23
	s_waitcnt lgkmcnt(0)
	v_bfe_u32 v19, v40, 16, 1
	v_lshrrev_b32_e32 v5, 16, v5
	v_add3_u32 v19, v40, v19, s23
	v_or_b32_e32 v42, s6, v10
	v_and_or_b32 v23, v19, s101, v5
	v_ashrrev_i32_e32 v43, 31, v42
	v_bfe_u32 v5, v29, 16, 1
	v_lshlrev_b64 v[42:43], 11, v[42:43]
	v_add3_u32 v5, v29, v5, s23
	v_bfe_u32 v19, v25, 16, 1
	v_lshl_add_u64 v[42:43], v[26:27], 0, v[42:43]
	v_lshrrev_b32_e32 v5, 16, v5
	v_add3_u32 v19, v25, v19, s23
	global_store_dwordx4 v[42:43], v[20:23], off
	v_or_b32_e32 v24, s6, v11
	v_ashrrev_i32_e32 v25, 31, v24
	v_and_or_b32 v20, v19, s101, v5
	v_bfe_u32 v5, v31, 16, 1
	v_add3_u32 v5, v31, v5, s23
	v_bfe_u32 v19, v33, 16, 1
	v_lshrrev_b32_e32 v5, 16, v5
	v_add3_u32 v19, v33, v19, s23
	v_and_or_b32 v21, v19, s101, v5
	v_bfe_u32 v5, v35, 16, 1
	v_add3_u32 v5, v35, v5, s23
	v_bfe_u32 v19, v37, 16, 1
	v_lshrrev_b32_e32 v5, 16, v5
	v_add3_u32 v19, v37, v19, s23
	v_and_or_b32 v22, v19, s101, v5
	v_bfe_u32 v5, v39, 16, 1
	v_add3_u32 v5, v39, v5, s23
	v_bfe_u32 v19, v41, 16, 1
	v_lshrrev_b32_e32 v5, 16, v5
	v_add3_u32 v19, v41, v19, s23
	v_lshlrev_b64 v[24:25], 11, v[24:25]
	v_and_or_b32 v23, v19, s101, v5
	v_lshl_add_u64 v[24:25], v[26:27], 0, v[24:25]
	global_store_dwordx4 v[24:25], v[20:23], off
	s_waitcnt lgkmcnt(0)

.Ltr1_316:
	s_ashr_i32 s0, s12, 31
	s_lshr_b32 s0, s0, 27
	s_add_i32 s0, s12, s0
	s_and_b32 s1, s0, 0x7ffffe0
	s_sub_i32 s1, s12, s1
	s_lshl_b32 s3, s8, 22
	s_add_u32 s3, s52, s3
	s_addc_u32 s7, s53, 0
	s_lshl_b32 s6, s8, 21
	s_add_u32 s9, s19, s6
	s_addc_u32 s8, s22, 0
	s_lshl_b32 s0, s0, 1
	s_and_b32 s6, s0, 0xffffffc0
	s_lshl_b32 s0, s1, 5
	s_ashr_i32 s1, s0, 31
	v_or_b32_e32 v20, s6, v1
	s_lshl_b64 s[12:13], s[0:1], 2
	s_add_u32 s12, s3, s12
	v_or_b32_e32 v26, 2, v20
	v_or_b32_e32 v28, 4, v20
	v_or_b32_e32 v30, 6, v20
	v_or_b32_e32 v32, 8, v20
	v_or_b32_e32 v34, 10, v20
	v_or_b32_e32 v36, 12, v20
	v_or_b32_e32 v38, 14, v20
	s_addc_u32 s13, s7, s13
	v_ashrrev_i32_e32 v21, 31, v20
	v_ashrrev_i32_e32 v27, 31, v26
	v_ashrrev_i32_e32 v29, 31, v28
	v_ashrrev_i32_e32 v31, 31, v30
	v_ashrrev_i32_e32 v33, 31, v32
	v_ashrrev_i32_e32 v35, 31, v34
	v_ashrrev_i32_e32 v37, 31, v36
	v_ashrrev_i32_e32 v39, 31, v38
	v_lshl_add_u64 v[22:23], s[12:13], 0, v[2:3]
	v_lshlrev_b64 v[24:25], 12, v[20:21]
	v_lshlrev_b64 v[26:27], 12, v[26:27]
	v_lshlrev_b64 v[28:29], 12, v[28:29]
	v_lshlrev_b64 v[30:31], 12, v[30:31]
	v_lshlrev_b64 v[32:33], 12, v[32:33]
	v_lshlrev_b64 v[34:35], 12, v[34:35]
	v_lshlrev_b64 v[36:37], 12, v[36:37]
	v_lshlrev_b64 v[38:39], 12, v[38:39]
	v_lshl_add_u64 v[24:25], v[22:23], 0, v[24:25]
	v_lshl_add_u64 v[26:27], v[22:23], 0, v[26:27]
	v_lshl_add_u64 v[28:29], v[22:23], 0, v[28:29]
	v_lshl_add_u64 v[30:31], v[22:23], 0, v[30:31]
	v_lshl_add_u64 v[32:33], v[22:23], 0, v[32:33]
	v_lshl_add_u64 v[34:35], v[22:23], 0, v[34:35]
	v_lshl_add_u64 v[36:37], v[22:23], 0, v[36:37]
	v_lshl_add_u64 v[38:39], v[22:23], 0, v[38:39]
	global_load_dword v5, v[24:25], off nt
	global_load_dword v19, v[26:27], off nt
	global_load_dword v40, v[28:29], off nt
	global_load_dword v41, v[30:31], off nt
	global_load_dword v42, v[32:33], off nt
	global_load_dword v43, v[34:35], off nt
	global_load_dword v44, v[36:37], off nt
	global_load_dword v45, v[38:39], off nt
	v_or_b32_e32 v24, 16, v20
	v_or_b32_e32 v26, 18, v20
	v_or_b32_e32 v28, 20, v20
	v_or_b32_e32 v30, 22, v20
	v_or_b32_e32 v32, 24, v20
	v_or_b32_e32 v34, 26, v20
	v_or_b32_e32 v36, 28, v20
	v_or_b32_e32 v38, 30, v20
	v_ashrrev_i32_e32 v25, 31, v24
	v_ashrrev_i32_e32 v27, 31, v26
	v_ashrrev_i32_e32 v29, 31, v28
	v_ashrrev_i32_e32 v31, 31, v30
	v_ashrrev_i32_e32 v33, 31, v32
	v_ashrrev_i32_e32 v35, 31, v34
	v_ashrrev_i32_e32 v37, 31, v36
	v_ashrrev_i32_e32 v39, 31, v38
	v_lshlrev_b64 v[24:25], 12, v[24:25]
	v_lshlrev_b64 v[26:27], 12, v[26:27]
	v_lshlrev_b64 v[28:29], 12, v[28:29]
	v_lshlrev_b64 v[30:31], 12, v[30:31]
	v_lshlrev_b64 v[32:33], 12, v[32:33]
	v_lshlrev_b64 v[34:35], 12, v[34:35]
	v_lshlrev_b64 v[36:37], 12, v[36:37]
	v_lshlrev_b64 v[38:39], 12, v[38:39]
	v_lshl_add_u64 v[24:25], v[22:23], 0, v[24:25]
	v_lshl_add_u64 v[26:27], v[22:23], 0, v[26:27]
	v_lshl_add_u64 v[28:29], v[22:23], 0, v[28:29]
	v_lshl_add_u64 v[30:31], v[22:23], 0, v[30:31]
	v_lshl_add_u64 v[32:33], v[22:23], 0, v[32:33]
	v_lshl_add_u64 v[34:35], v[22:23], 0, v[34:35]
	v_lshl_add_u64 v[36:37], v[22:23], 0, v[36:37]
	v_lshl_add_u64 v[38:39], v[22:23], 0, v[38:39]
	global_load_dword v46, v[24:25], off nt
	global_load_dword v47, v[26:27], off nt
	global_load_dword v48, v[28:29], off nt
	global_load_dword v49, v[30:31], off nt
	global_load_dword v50, v[32:33], off nt
	global_load_dword v51, v[34:35], off nt
	global_load_dword v52, v[36:37], off nt
	global_load_dword v53, v[38:39], off nt
	v_or_b32_e32 v24, 32, v20
	v_or_b32_e32 v26, 34, v20
	v_or_b32_e32 v28, 36, v20
	v_or_b32_e32 v30, 38, v20
	v_or_b32_e32 v32, 40, v20
	v_or_b32_e32 v34, 42, v20
	v_or_b32_e32 v36, 44, v20
	v_or_b32_e32 v38, 46, v20
	v_ashrrev_i32_e32 v25, 31, v24
	v_ashrrev_i32_e32 v27, 31, v26
	v_ashrrev_i32_e32 v29, 31, v28
	v_ashrrev_i32_e32 v31, 31, v30
	v_ashrrev_i32_e32 v33, 31, v32
	v_ashrrev_i32_e32 v35, 31, v34
	v_ashrrev_i32_e32 v37, 31, v36
	v_ashrrev_i32_e32 v39, 31, v38
	v_lshlrev_b64 v[24:25], 12, v[24:25]
	v_lshlrev_b64 v[26:27], 12, v[26:27]
	v_lshlrev_b64 v[28:29], 12, v[28:29]
	v_lshlrev_b64 v[30:31], 12, v[30:31]
	v_lshlrev_b64 v[32:33], 12, v[32:33]
	v_lshlrev_b64 v[34:35], 12, v[34:35]
	v_lshlrev_b64 v[36:37], 12, v[36:37]
	v_lshlrev_b64 v[38:39], 12, v[38:39]
	v_lshl_add_u64 v[24:25], v[22:23], 0, v[24:25]
	v_lshl_add_u64 v[26:27], v[22:23], 0, v[26:27]
	v_lshl_add_u64 v[28:29], v[22:23], 0, v[28:29]
	v_lshl_add_u64 v[30:31], v[22:23], 0, v[30:31]
	v_lshl_add_u64 v[32:33], v[22:23], 0, v[32:33]
	v_lshl_add_u64 v[34:35], v[22:23], 0, v[34:35]
	v_lshl_add_u64 v[36:37], v[22:23], 0, v[36:37]
	v_lshl_add_u64 v[38:39], v[22:23], 0, v[38:39]
	global_load_dword v54, v[24:25], off nt
	global_load_dword v55, v[26:27], off nt
	global_load_dword v56, v[28:29], off nt
	global_load_dword v57, v[30:31], off nt
	global_load_dword v58, v[32:33], off nt
	global_load_dword v59, v[34:35], off nt
	global_load_dword v60, v[36:37], off nt
	s_nop 0
	global_load_dword v38, v[38:39], off nt
	v_or_b32_e32 v24, 48, v20
	v_or_b32_e32 v26, 50, v20
	v_or_b32_e32 v28, 52, v20
	v_or_b32_e32 v30, 54, v20
	v_or_b32_e32 v32, 56, v20
	v_or_b32_e32 v34, 58, v20
	v_or_b32_e32 v36, 60, v20
	v_or_b32_e32 v20, 62, v20
	v_ashrrev_i32_e32 v25, 31, v24
	v_ashrrev_i32_e32 v27, 31, v26
	v_ashrrev_i32_e32 v29, 31, v28
	v_ashrrev_i32_e32 v21, 31, v20
	v_lshlrev_b64 v[24:25], 12, v[24:25]
	v_lshlrev_b64 v[26:27], 12, v[26:27]
	v_lshlrev_b64 v[28:29], 12, v[28:29]
	v_ashrrev_i32_e32 v31, 31, v30
	v_ashrrev_i32_e32 v33, 31, v32
	v_ashrrev_i32_e32 v35, 31, v34
	v_ashrrev_i32_e32 v37, 31, v36
	v_lshlrev_b64 v[20:21], 12, v[20:21]
	v_lshl_add_u64 v[24:25], v[22:23], 0, v[24:25]
	v_lshl_add_u64 v[26:27], v[22:23], 0, v[26:27]
	v_lshl_add_u64 v[28:29], v[22:23], 0, v[28:29]
	v_lshlrev_b64 v[30:31], 12, v[30:31]
	v_lshlrev_b64 v[32:33], 12, v[32:33]
	v_lshlrev_b64 v[34:35], 12, v[34:35]
	v_lshlrev_b64 v[36:37], 12, v[36:37]
	v_lshl_add_u64 v[20:21], v[22:23], 0, v[20:21]
	v_lshl_add_u64 v[30:31], v[22:23], 0, v[30:31]
	v_lshl_add_u64 v[32:33], v[22:23], 0, v[32:33]
	v_lshl_add_u64 v[34:35], v[22:23], 0, v[34:35]
	v_lshl_add_u64 v[36:37], v[22:23], 0, v[36:37]
	global_load_dword v22, v[24:25], off nt
	global_load_dword v23, v[26:27], off nt
	s_nop 0
	global_load_dword v24, v[28:29], off nt
	global_load_dword v25, v[30:31], off nt
	global_load_dword v26, v[32:33], off nt
	global_load_dword v27, v[34:35], off nt
	s_nop 0
	global_load_dword v28, v[36:37], off nt
	s_nop 0
	global_load_dword v20, v[20:21], off nt
	s_waitcnt vmcnt(0)
	ds_write2_b32 v6, v5, v19 offset1:66
	ds_write2_b32 v6, v40, v41 offset0:132 offset1:198
	ds_write2_b32 v12, v42, v43 offset0:8 offset1:74
	ds_write2_b32 v12, v44, v45 offset0:140 offset1:206
	ds_write2_b32 v13, v46, v47 offset0:16 offset1:82
	ds_write2_b32 v13, v48, v49 offset0:148 offset1:214
	ds_write2_b32 v14, v50, v51 offset0:24 offset1:90
	ds_write2_b32 v14, v52, v53 offset0:156 offset1:222
	ds_write2_b32 v15, v54, v55 offset0:32 offset1:98
	ds_write2_b32 v15, v56, v57 offset0:164 offset1:230
	ds_write2_b32 v16, v58, v59 offset0:40 offset1:106
	ds_write2_b32 v16, v60, v38 offset0:172 offset1:238
	ds_write2_b32 v17, v22, v23 offset0:48 offset1:114
	ds_write2_b32 v17, v24, v25 offset0:180 offset1:246
	ds_write2_b32 v18, v26, v27 offset0:56 offset1:122
	ds_write2_b32 v18, v28, v20 offset0:188 offset1:254
	s_waitcnt lgkmcnt(0)
	ds_read2_b32 v[24:25], v8 offset1:8
	s_ashr_i32 s7, s6, 31
	ds_read2_b32 v[28:29], v8 offset0:33 offset1:41
	s_lshl_b64 s[6:7], s[6:7], 1
	s_add_u32 s6, s9, s6
	ds_read2_b32 v[30:31], v8 offset0:66 offset1:74
	s_addc_u32 s7, s8, s7
	v_mov_b32_e32 v5, v3
	ds_read2_b32 v[32:33], v8 offset0:99 offset1:107
	v_lshl_add_u64 v[26:27], s[6:7], 0, v[4:5]
	s_waitcnt lgkmcnt(3)
	v_bfe_u32 v5, v24, 16, 1
	v_add3_u32 v5, v24, v5, s23
	s_waitcnt lgkmcnt(2)
	v_bfe_u32 v19, v28, 16, 1
	ds_read2_b32 v[34:35], v8 offset0:132 offset1:140
	v_lshrrev_b32_e32 v5, 16, v5
	v_add3_u32 v19, v28, v19, s23
	ds_read2_b32 v[36:37], v8 offset0:165 offset1:173
	v_and_or_b32 v20, v19, s101, v5
	s_waitcnt lgkmcnt(3)
	v_bfe_u32 v5, v30, 16, 1
	v_add3_u32 v5, v30, v5, s23
	s_waitcnt lgkmcnt(2)
	v_bfe_u32 v19, v32, 16, 1
	ds_read2_b32 v[38:39], v8 offset0:198 offset1:206
	v_lshrrev_b32_e32 v5, 16, v5
	v_add3_u32 v19, v32, v19, s23
	ds_read2_b32 v[40:41], v8 offset0:231 offset1:239
	v_and_or_b32 v21, v19, s101, v5
	s_waitcnt lgkmcnt(3)
	v_bfe_u32 v5, v34, 16, 1
	v_add3_u32 v5, v34, v5, s23
	s_waitcnt lgkmcnt(2)
	v_bfe_u32 v19, v36, 16, 1
	v_lshrrev_b32_e32 v5, 16, v5
	v_add3_u32 v19, v36, v19, s23
	v_and_or_b32 v22, v19, s101, v5
	s_waitcnt lgkmcnt(1)
	v_bfe_u32 v5, v38, 16, 1
	v_add3_u32 v5, v38, v5, s23
	s_waitcnt lgkmcnt(0)
	v_bfe_u32 v19, v40, 16, 1
	v_lshrrev_b32_e32 v5, 16, v5
	v_add3_u32 v19, v40, v19, s23
	v_or_b32_e32 v42, s0, v7
	v_and_or_b32 v23, v19, s101, v5
	v_ashrrev_i32_e32 v43, 31, v42
	v_bfe_u32 v5, v25, 16, 1
	v_lshlrev_b64 v[42:43], 11, v[42:43]
	v_add3_u32 v5, v25, v5, s23
	v_bfe_u32 v19, v29, 16, 1
	v_lshl_add_u64 v[42:43], v[26:27], 0, v[42:43]
	v_lshrrev_b32_e32 v5, 16, v5
	v_add3_u32 v19, v29, v19, s23
	global_store_dwordx4 v[42:43], v[20:23], off
	v_or_b32_e32 v24, s0, v9
	v_ashrrev_i32_e32 v25, 31, v24
	v_and_or_b32 v20, v19, s101, v5
	v_bfe_u32 v5, v31, 16, 1
	v_add3_u32 v5, v31, v5, s23
	v_bfe_u32 v19, v33, 16, 1
	v_lshrrev_b32_e32 v5, 16, v5
	v_add3_u32 v19, v33, v19, s23
	v_and_or_b32 v21, v19, s101, v5
	v_bfe_u32 v5, v35, 16, 1
	v_add3_u32 v5, v35, v5, s23
	v_bfe_u32 v19, v37, 16, 1
	v_lshrrev_b32_e32 v5, 16, v5
	v_add3_u32 v19, v37, v19, s23
	v_and_or_b32 v22, v19, s101, v5
	v_bfe_u32 v5, v39, 16, 1
	v_add3_u32 v5, v39, v5, s23
	v_bfe_u32 v19, v41, 16, 1
	v_lshrrev_b32_e32 v5, 16, v5
	v_add3_u32 v19, v41, v19, s23
	v_lshlrev_b64 v[24:25], 11, v[24:25]
	v_and_or_b32 v23, v19, s101, v5
	ds_read2_b32 v[28:29], v8 offset0:16 offset1:24
	v_lshl_add_u64 v[24:25], v[26:27], 0, v[24:25]
	global_store_dwordx4 v[24:25], v[20:23], off
	ds_read2_b32 v[24:25], v8 offset0:49 offset1:57
	ds_read2_b32 v[30:31], v8 offset0:82 offset1:90
	ds_read2_b32 v[32:33], v8 offset0:115 offset1:123
	s_waitcnt lgkmcnt(3)
	v_bfe_u32 v5, v28, 16, 1
	v_add3_u32 v5, v28, v5, s23
	s_waitcnt lgkmcnt(2)
	v_bfe_u32 v19, v24, 16, 1
	ds_read2_b32 v[34:35], v8 offset0:148 offset1:156
	v_lshrrev_b32_e32 v5, 16, v5
	v_add3_u32 v19, v24, v19, s23
	ds_read2_b32 v[36:37], v8 offset0:181 offset1:189
	v_and_or_b32 v20, v19, s101, v5
	s_waitcnt lgkmcnt(3)
	v_bfe_u32 v5, v30, 16, 1
	v_add3_u32 v5, v30, v5, s23
	s_waitcnt lgkmcnt(2)
	v_bfe_u32 v19, v32, 16, 1
	ds_read2_b32 v[38:39], v8 offset0:214 offset1:222
	v_lshrrev_b32_e32 v5, 16, v5
	v_add3_u32 v19, v32, v19, s23
	ds_read2_b32 v[40:41], v8 offset0:247 offset1:255
	v_and_or_b32 v21, v19, s101, v5
	s_waitcnt lgkmcnt(3)
	v_bfe_u32 v5, v34, 16, 1
	v_add3_u32 v5, v34, v5, s23
	s_waitcnt lgkmcnt(2)
	v_bfe_u32 v19, v36, 16, 1
	v_lshrrev_b32_e32 v5, 16, v5
	v_add3_u32 v19, v36, v19, s23
	v_and_or_b32 v22, v19, s101, v5
	s_waitcnt lgkmcnt(1)
	v_bfe_u32 v5, v38, 16, 1
	v_add3_u32 v5, v38, v5, s23
	s_waitcnt lgkmcnt(0)
	v_bfe_u32 v19, v40, 16, 1
	v_lshrrev_b32_e32 v5, 16, v5
	v_add3_u32 v19, v40, v19, s23
	v_or_b32_e32 v42, s0, v10
	v_and_or_b32 v23, v19, s101, v5
	v_ashrrev_i32_e32 v43, 31, v42
	v_bfe_u32 v5, v29, 16, 1
	v_lshlrev_b64 v[42:43], 11, v[42:43]
	v_add3_u32 v5, v29, v5, s23
	v_bfe_u32 v19, v25, 16, 1
	v_lshl_add_u64 v[42:43], v[26:27], 0, v[42:43]
	v_lshrrev_b32_e32 v5, 16, v5
	v_add3_u32 v19, v25, v19, s23
	global_store_dwordx4 v[42:43], v[20:23], off
	v_or_b32_e32 v24, s0, v11
	v_ashrrev_i32_e32 v25, 31, v24
	v_and_or_b32 v20, v19, s101, v5
	v_bfe_u32 v5, v31, 16, 1
	v_add3_u32 v5, v31, v5, s23
	v_bfe_u32 v19, v33, 16, 1
	v_lshrrev_b32_e32 v5, 16, v5
	v_add3_u32 v19, v33, v19, s23
	v_and_or_b32 v21, v19, s101, v5
	v_bfe_u32 v5, v35, 16, 1
	v_add3_u32 v5, v35, v5, s23
	v_bfe_u32 v19, v37, 16, 1
	v_lshrrev_b32_e32 v5, 16, v5
	v_add3_u32 v19, v37, v19, s23
	v_and_or_b32 v22, v19, s101, v5
	v_bfe_u32 v5, v39, 16, 1
	v_add3_u32 v5, v39, v5, s23
	v_bfe_u32 v19, v41, 16, 1
	v_lshrrev_b32_e32 v5, 16, v5
	v_add3_u32 v19, v41, v19, s23
	v_lshlrev_b64 v[24:25], 11, v[24:25]
	v_and_or_b32 v23, v19, s101, v5
	v_lshl_add_u64 v[24:25], v[26:27], 0, v[24:25]
	global_store_dwordx4 v[24:25], v[20:23], off
	s_waitcnt lgkmcnt(0)
	s_branch .Ltr1_303
